# WG stagger config H: 8 groups (bits 3,4,5; 0.9us steps) in phases 1 and 8; 4 groups 3.5us steps in phases 6 and 11
# speedup vs baseline: 1.0103x; 1.0103x over previous
;   DI bf16_t* wt_in0() const { return (bf16_t*)(ws + OFF_WT_IN0); }
;   DI bf16_t* h() const { return (bf16_t*)(ws + OFF_H); }
; DI void phase_gemm_in0(const Params& p, char* smem) {
;   u32x4 ra[4], rb[4]; bool pre = false;
;   for (int t = blockIdx.x; t < 64 * 16; t += gridDim.x) {
;     const int mt = t & 63, nt = t >> 6, tn = t + gridDim.x;
;     const bool has_next = tn < 64 * 16;
;     const GTile tl{p.h(), D, p.wt_in0(), D, D, mt * 256, nt * 256}, nx{p.h(), D, p.wt_in0(), D, D, (tn & 63) * 256, (tn >> 6) * 256};
.Lgs_185:
	s_or_b64 exec, exec, s[0:1]
	s_bitcmp1_b32 s84, 3
	s_cbranch_scc0 .Lstag_1_0
	s_sleep 32
.Lstag_1_0:
	s_bitcmp1_b32 s84, 4
	s_cbranch_scc0 .Lstag_1_1
	s_sleep 64
.Lstag_1_1:
	s_bitcmp1_b32 s84, 5
	s_cbranch_scc0 .Lstag_1_2
	s_sleep 127
